# in-projection and SwiGLU GEMM K-loops: first K-iteration peeled with zero accumulator input, per-unit accumulator zeroing moves removed
# speedup vs baseline: 1.0101x; 1.0101x over previous
.LBB0_291:
	s_ashr_i32 s29, s28, 31
	s_lshl_b64 s[30:31], s[28:29], 19
	s_add_u32 s30, s3, s30
	s_addc_u32 s31, s4, s31
	s_and_b64 s[34:35], s[6:7], exec
	s_cselect_b32 s29, s31, s39
	s_cselect_b32 s37, s30, s38
	s_ashr_i32 s27, s26, 31
	s_lshl_b64 s[34:35], s[26:27], 19
	s_add_u32 s34, s5, s34
	s_addc_u32 s35, s44, s35
	s_and_b64 s[42:43], s[6:7], exec
	s_cselect_b32 s27, s35, s41
	s_cselect_b32 s61, s34, s40
	s_add_u32 s38, s38, 0x40080
	s_addc_u32 s39, s39, 0
	s_add_u32 s62, s40, 0x100
	v_mov_b32_e32 v0, 0
	s_addc_u32 s63, s41, 0
	s_mov_b32 s65, -2
	ds_read_b128 v[146:149], v155
	ds_read_b128 v[158:161], v155 offset:1024
	ds_read_b128 v[162:165], v155 offset:2048
	ds_read_b128 v[166:169], v155 offset:3072
	ds_read_b128 v[170:173], v156
	ds_read_b128 v[176:179], v156 offset:1024
	ds_read_b128 v[180:183], v156 offset:2048
	ds_read_b128 v[184:187], v156 offset:3072
	s_add_u32 s40, s38, 0xfffc0080
	s_addc_u32 s41, s39, -1
	s_cmp_eq_u32 s65, 12
	s_cselect_b32 s43, s29, s41
	s_cselect_b32 s42, s37, s40
	s_cselect_b32 s41, s27, s63
	s_cselect_b32 s40, s61, s62
	v_lshl_add_u64 v[150:151], s[38:39], 0, v[138:139]
	s_add_i32 m0, s48, 0xc000
	ds_read_b128 v[188:191], v157
	ds_read_b128 v[192:195], v157 offset:1024
	ds_read_b128 v[196:199], v157 offset:2048
	ds_read_b128 v[200:203], v157 offset:3072
	ds_read_b128 v[204:207], v157 offset:4096
	ds_read_b128 v[208:211], v157 offset:5120
	ds_read_b128 v[212:215], v157 offset:6144
	ds_read_b128 v[216:219], v157 offset:7168
	global_load_lds_dwordx4 v[150:151], off
	v_lshl_add_u64 v[150:151], s[38:39], 0, v[140:141]
	s_add_i32 m0, s48, 0xe000
	s_nop 0
	global_load_lds_dwordx4 v[150:151], off
	s_waitcnt vmcnt(8)
	s_waitcnt lgkmcnt(0)
	s_barrier
	s_setprio 1
	s_waitcnt lgkmcnt(0)
	v_mfma_f32_16x16x32_bf16 v[124:127], v[146:149], v[188:191], 0
	v_mfma_f32_16x16x32_bf16 v[120:123], v[162:165], v[188:191], 0
	v_mfma_f32_16x16x32_bf16 v[116:119], v[146:149], v[196:199], 0
	v_mfma_f32_16x16x32_bf16 v[108:111], v[162:165], v[196:199], 0
	v_mfma_f32_16x16x32_bf16 v[100:103], v[146:149], v[204:207], 0
	v_mfma_f32_16x16x32_bf16 v[92:95], v[162:165], v[204:207], 0
	v_mfma_f32_16x16x32_bf16 v[84:87], v[146:149], v[212:215], 0
	v_mfma_f32_16x16x32_bf16 v[76:79], v[162:165], v[212:215], 0
	v_mfma_f32_16x16x32_bf16 v[124:127], v[158:161], v[192:195], v[124:127]
	v_mfma_f32_16x16x32_bf16 v[120:123], v[166:169], v[192:195], v[120:123]
	v_mfma_f32_16x16x32_bf16 v[116:119], v[158:161], v[200:203], v[116:119]
	v_mfma_f32_16x16x32_bf16 v[108:111], v[166:169], v[200:203], v[108:111]
	v_mfma_f32_16x16x32_bf16 v[100:103], v[158:161], v[208:211], v[100:103]
	v_mfma_f32_16x16x32_bf16 v[92:95], v[166:169], v[208:211], v[92:95]
	v_mfma_f32_16x16x32_bf16 v[84:87], v[158:161], v[216:219], v[84:87]
	v_mfma_f32_16x16x32_bf16 v[76:79], v[166:169], v[216:219], v[76:79]
	s_setprio 0
	s_setprio 1
	v_mfma_f32_16x16x32_bf16 v[112:115], v[170:173], v[188:191], 0
	v_mfma_f32_16x16x32_bf16 v[104:107], v[180:183], v[188:191], 0
	v_mfma_f32_16x16x32_bf16 v[96:99], v[170:173], v[196:199], 0
	v_mfma_f32_16x16x32_bf16 v[88:91], v[180:183], v[196:199], 0
	v_mfma_f32_16x16x32_bf16 v[80:83], v[170:173], v[204:207], 0
	v_mfma_f32_16x16x32_bf16 v[72:75], v[180:183], v[204:207], 0
	v_mfma_f32_16x16x32_bf16 v[68:71], v[170:173], v[212:215], 0
	v_mfma_f32_16x16x32_bf16 v[64:67], v[180:183], v[212:215], 0
	v_mfma_f32_16x16x32_bf16 v[112:115], v[176:179], v[192:195], v[112:115]
	v_mfma_f32_16x16x32_bf16 v[104:107], v[184:187], v[192:195], v[104:107]
	v_mfma_f32_16x16x32_bf16 v[96:99], v[176:179], v[200:203], v[96:99]
	v_mfma_f32_16x16x32_bf16 v[88:91], v[184:187], v[200:203], v[88:91]
	v_mfma_f32_16x16x32_bf16 v[80:83], v[176:179], v[208:211], v[80:83]
	v_mfma_f32_16x16x32_bf16 v[72:75], v[184:187], v[208:211], v[72:75]
	v_mfma_f32_16x16x32_bf16 v[68:71], v[176:179], v[216:219], v[68:71]
	v_mfma_f32_16x16x32_bf16 v[64:67], v[184:187], v[216:219], v[64:67]
	s_setprio 0
	s_barrier
	s_add_i32 s68, s57, s45
	v_lshl_add_u64 v[150:151], s[40:41], 0, v[132:133]
	s_mov_b32 m0, s68
	ds_read_b128 v[188:191], v157 offset:16384
	ds_read_b128 v[192:195], v157 offset:17408
	ds_read_b128 v[196:199], v157 offset:18432
	ds_read_b128 v[200:203], v157 offset:19456
	ds_read_b128 v[204:207], v157 offset:20480
	ds_read_b128 v[208:211], v157 offset:21504
	ds_read_b128 v[212:215], v157 offset:22528
	ds_read_b128 v[216:219], v157 offset:23552
	global_load_lds_dwordx4 v[150:151], off
	s_add_i32 m0, s68, 0x2000
	s_add_u32 s68, s40, 0x40000
	v_lshl_add_u64 v[220:221], s[40:41], 0, v[128:129]
	s_addc_u32 s69, s41, 0
	s_add_i32 s72, s58, s45
	global_load_lds_dwordx4 v[220:221], off
	v_lshl_add_u64 v[222:223], s[68:69], 0, v[132:133]
	s_mov_b32 m0, s72
	v_lshl_add_u64 v[224:225], s[42:43], 0, v[130:131]
	global_load_lds_dwordx4 v[222:223], off
	v_lshl_add_u64 v[222:223], s[68:69], 0, v[128:129]
	s_add_i32 m0, s72, 0x2000
	s_nop 0
	global_load_lds_dwordx4 v[222:223], off
	v_lshl_add_u64 v[222:223], s[42:43], 0, v[134:135]
	s_mov_b32 m0, s48
	s_nop 0
	global_load_lds_dwordx4 v[222:223], off
	s_mov_b32 m0, s49
	s_nop 0
	global_load_lds_dwordx4 v[224:225], off
	s_waitcnt vmcnt(8)
	s_waitcnt lgkmcnt(0)
	s_barrier
	s_setprio 1
	s_waitcnt lgkmcnt(0)
	v_mfma_f32_16x16x32_bf16 v[60:63], v[146:149], v[188:191], 0
	v_mfma_f32_16x16x32_bf16 v[56:59], v[162:165], v[188:191], 0
	v_mfma_f32_16x16x32_bf16 v[52:55], v[146:149], v[196:199], 0
	v_mfma_f32_16x16x32_bf16 v[44:47], v[162:165], v[196:199], 0
	v_mfma_f32_16x16x32_bf16 v[36:39], v[146:149], v[204:207], 0
	v_mfma_f32_16x16x32_bf16 v[28:31], v[162:165], v[204:207], 0
	v_mfma_f32_16x16x32_bf16 v[20:23], v[146:149], v[212:215], 0
	v_mfma_f32_16x16x32_bf16 v[12:15], v[162:165], v[212:215], 0
	v_mfma_f32_16x16x32_bf16 v[60:63], v[158:161], v[192:195], v[60:63]
	v_mfma_f32_16x16x32_bf16 v[56:59], v[166:169], v[192:195], v[56:59]
	v_mfma_f32_16x16x32_bf16 v[52:55], v[158:161], v[200:203], v[52:55]
	v_mfma_f32_16x16x32_bf16 v[44:47], v[166:169], v[200:203], v[44:47]
	v_mfma_f32_16x16x32_bf16 v[36:39], v[158:161], v[208:211], v[36:39]
	v_mfma_f32_16x16x32_bf16 v[28:31], v[166:169], v[208:211], v[28:31]
	v_mfma_f32_16x16x32_bf16 v[20:23], v[158:161], v[216:219], v[20:23]
	v_mfma_f32_16x16x32_bf16 v[12:15], v[166:169], v[216:219], v[12:15]
	s_setprio 0
	s_setprio 1
	v_mfma_f32_16x16x32_bf16 v[48:51], v[170:173], v[188:191], 0
	v_mfma_f32_16x16x32_bf16 v[40:43], v[180:183], v[188:191], 0
	v_mfma_f32_16x16x32_bf16 v[32:35], v[170:173], v[196:199], 0
	v_mfma_f32_16x16x32_bf16 v[24:27], v[180:183], v[196:199], 0
	v_mfma_f32_16x16x32_bf16 v[16:19], v[170:173], v[204:207], 0
	v_mfma_f32_16x16x32_bf16 v[8:11], v[180:183], v[204:207], 0
	v_mfma_f32_16x16x32_bf16 v[4:7], v[170:173], v[212:215], 0
	v_mfma_f32_16x16x32_bf16 v[0:3], v[180:183], v[212:215], 0
	v_mfma_f32_16x16x32_bf16 v[48:51], v[176:179], v[192:195], v[48:51]
	v_mfma_f32_16x16x32_bf16 v[40:43], v[184:187], v[192:195], v[40:43]
	v_mfma_f32_16x16x32_bf16 v[32:35], v[176:179], v[200:203], v[32:35]
	v_mfma_f32_16x16x32_bf16 v[24:27], v[184:187], v[200:203], v[24:27]
	v_mfma_f32_16x16x32_bf16 v[16:19], v[176:179], v[208:211], v[16:19]
	v_mfma_f32_16x16x32_bf16 v[8:11], v[184:187], v[208:211], v[8:11]
	v_mfma_f32_16x16x32_bf16 v[4:7], v[176:179], v[216:219], v[4:7]
	v_mfma_f32_16x16x32_bf16 v[0:3], v[184:187], v[216:219], v[0:3]
	s_setprio 0
	s_barrier
	s_add_i32 s68, 0, 0x18000
	s_add_i32 s69, 0, 0x1c000
	v_add_u32_e32 v166, s68, v153
	v_add_u32_e32 v184, s69, v153
	ds_read_b128 v[146:149], v166
	ds_read_b128 v[158:161], v166 offset:1024
	ds_read_b128 v[162:165], v166 offset:2048
	ds_read_b128 v[166:169], v166 offset:3072
	ds_read_b128 v[170:173], v184
	ds_read_b128 v[176:179], v184 offset:1024
	ds_read_b128 v[180:183], v184 offset:2048
	ds_read_b128 v[184:187], v184 offset:3072
	s_add_u32 s42, s42, 0x40000
	s_addc_u32 s43, s43, 0
	s_mov_b32 m0, s50
	v_lshl_add_u64 v[226:227], s[42:43], 0, v[134:135]
	ds_read_b128 v[188:191], v157 offset:32768
	ds_read_b128 v[192:195], v157 offset:33792
	ds_read_b128 v[196:199], v157 offset:34816
	ds_read_b128 v[200:203], v157 offset:35840
	ds_read_b128 v[204:207], v157 offset:36864
	ds_read_b128 v[208:211], v157 offset:37888
	ds_read_b128 v[212:215], v157 offset:38912
	ds_read_b128 v[216:219], v157 offset:39936
	global_load_lds_dwordx4 v[226:227], off
	v_lshl_add_u64 v[226:227], s[42:43], 0, v[130:131]
	s_mov_b32 m0, s51
	s_nop 0
	global_load_lds_dwordx4 v[226:227], off
	s_waitcnt vmcnt(8)
	s_waitcnt lgkmcnt(0)
	s_barrier
	s_setprio 1
	s_waitcnt lgkmcnt(0)
	v_mfma_f32_16x16x32_bf16 v[124:127], v[146:149], v[188:191], v[124:127]
	v_mfma_f32_16x16x32_bf16 v[120:123], v[162:165], v[188:191], v[120:123]
	v_mfma_f32_16x16x32_bf16 v[116:119], v[146:149], v[196:199], v[116:119]
	v_mfma_f32_16x16x32_bf16 v[108:111], v[162:165], v[196:199], v[108:111]
	v_mfma_f32_16x16x32_bf16 v[100:103], v[146:149], v[204:207], v[100:103]
	v_mfma_f32_16x16x32_bf16 v[92:95], v[162:165], v[204:207], v[92:95]
	v_mfma_f32_16x16x32_bf16 v[84:87], v[146:149], v[212:215], v[84:87]
	v_mfma_f32_16x16x32_bf16 v[76:79], v[162:165], v[212:215], v[76:79]
	v_mfma_f32_16x16x32_bf16 v[124:127], v[158:161], v[192:195], v[124:127]
	v_mfma_f32_16x16x32_bf16 v[120:123], v[166:169], v[192:195], v[120:123]
	v_mfma_f32_16x16x32_bf16 v[116:119], v[158:161], v[200:203], v[116:119]
	v_mfma_f32_16x16x32_bf16 v[108:111], v[166:169], v[200:203], v[108:111]
	v_mfma_f32_16x16x32_bf16 v[100:103], v[158:161], v[208:211], v[100:103]
	v_mfma_f32_16x16x32_bf16 v[92:95], v[166:169], v[208:211], v[92:95]
	v_mfma_f32_16x16x32_bf16 v[84:87], v[158:161], v[216:219], v[84:87]
	v_mfma_f32_16x16x32_bf16 v[76:79], v[166:169], v[216:219], v[76:79]
	s_setprio 0
	s_setprio 1
	v_mfma_f32_16x16x32_bf16 v[112:115], v[170:173], v[188:191], v[112:115]
	v_mfma_f32_16x16x32_bf16 v[104:107], v[180:183], v[188:191], v[104:107]
	v_mfma_f32_16x16x32_bf16 v[96:99], v[170:173], v[196:199], v[96:99]
	v_mfma_f32_16x16x32_bf16 v[88:91], v[180:183], v[196:199], v[88:91]
	v_mfma_f32_16x16x32_bf16 v[80:83], v[170:173], v[204:207], v[80:83]
	v_mfma_f32_16x16x32_bf16 v[72:75], v[180:183], v[204:207], v[72:75]
	v_mfma_f32_16x16x32_bf16 v[68:71], v[170:173], v[212:215], v[68:71]
	v_mfma_f32_16x16x32_bf16 v[64:67], v[180:183], v[212:215], v[64:67]
	v_mfma_f32_16x16x32_bf16 v[112:115], v[176:179], v[192:195], v[112:115]
	v_mfma_f32_16x16x32_bf16 v[104:107], v[184:187], v[192:195], v[104:107]
	v_mfma_f32_16x16x32_bf16 v[96:99], v[176:179], v[200:203], v[96:99]
	v_mfma_f32_16x16x32_bf16 v[88:91], v[184:187], v[200:203], v[88:91]
	v_mfma_f32_16x16x32_bf16 v[80:83], v[176:179], v[208:211], v[80:83]
	v_mfma_f32_16x16x32_bf16 v[72:75], v[184:187], v[208:211], v[72:75]
	v_mfma_f32_16x16x32_bf16 v[68:71], v[176:179], v[216:219], v[68:71]
	v_mfma_f32_16x16x32_bf16 v[64:67], v[184:187], v[216:219], v[64:67]
	s_setprio 0
	s_barrier
	s_add_i32 s42, s68, s45
	v_lshl_add_u64 v[150:151], v[150:151], 0, s[14:15]
	s_mov_b32 m0, s42
	ds_read_b128 v[188:191], v157 offset:49152
	ds_read_b128 v[192:195], v157 offset:50176
	ds_read_b128 v[196:199], v157 offset:51200
	ds_read_b128 v[200:203], v157 offset:52224
	ds_read_b128 v[204:207], v157 offset:53248
	ds_read_b128 v[208:211], v157 offset:54272
	ds_read_b128 v[212:215], v157 offset:55296
	ds_read_b128 v[216:219], v157 offset:56320
	global_load_lds_dwordx4 v[150:151], off
	s_add_i32 m0, s42, 0x2000
	s_add_u32 s40, s40, 0x40080
	v_lshl_add_u64 v[150:151], v[220:221], 0, s[14:15]
	s_addc_u32 s41, s41, 0
	s_add_i32 s42, s69, s45
	global_load_lds_dwordx4 v[150:151], off
	v_lshl_add_u64 v[150:151], s[40:41], 0, v[132:133]
	s_mov_b32 m0, s42
	s_nop 0
	global_load_lds_dwordx4 v[150:151], off
	v_lshl_add_u64 v[150:151], s[40:41], 0, v[128:129]
	s_add_i32 m0, s42, 0x2000
	s_nop 0
	global_load_lds_dwordx4 v[150:151], off
	v_lshl_add_u64 v[150:151], v[222:223], 0, s[14:15]
	s_mov_b32 m0, s53
	s_nop 0
	global_load_lds_dwordx4 v[150:151], off
	v_lshl_add_u64 v[150:151], v[224:225], 0, s[14:15]
	s_mov_b32 m0, s54
	s_nop 0
	global_load_lds_dwordx4 v[150:151], off
	s_waitcnt vmcnt(8)
	s_waitcnt lgkmcnt(0)
	s_barrier
	s_setprio 1
	s_waitcnt lgkmcnt(0)
	v_mfma_f32_16x16x32_bf16 v[60:63], v[146:149], v[188:191], v[60:63]
	v_mfma_f32_16x16x32_bf16 v[56:59], v[162:165], v[188:191], v[56:59]
	v_mfma_f32_16x16x32_bf16 v[52:55], v[146:149], v[196:199], v[52:55]
	v_mfma_f32_16x16x32_bf16 v[44:47], v[162:165], v[196:199], v[44:47]
	v_mfma_f32_16x16x32_bf16 v[36:39], v[146:149], v[204:207], v[36:39]
	v_mfma_f32_16x16x32_bf16 v[28:31], v[162:165], v[204:207], v[28:31]
	v_mfma_f32_16x16x32_bf16 v[20:23], v[146:149], v[212:215], v[20:23]
	v_mfma_f32_16x16x32_bf16 v[12:15], v[162:165], v[212:215], v[12:15]
	v_mfma_f32_16x16x32_bf16 v[60:63], v[158:161], v[192:195], v[60:63]
	v_mfma_f32_16x16x32_bf16 v[56:59], v[166:169], v[192:195], v[56:59]
	v_mfma_f32_16x16x32_bf16 v[52:55], v[158:161], v[200:203], v[52:55]
	v_mfma_f32_16x16x32_bf16 v[44:47], v[166:169], v[200:203], v[44:47]
	v_mfma_f32_16x16x32_bf16 v[36:39], v[158:161], v[208:211], v[36:39]
	v_mfma_f32_16x16x32_bf16 v[28:31], v[166:169], v[208:211], v[28:31]
	v_mfma_f32_16x16x32_bf16 v[20:23], v[158:161], v[216:219], v[20:23]
	v_mfma_f32_16x16x32_bf16 v[12:15], v[166:169], v[216:219], v[12:15]
	s_setprio 0
	s_setprio 1
	v_mfma_f32_16x16x32_bf16 v[48:51], v[170:173], v[188:191], v[48:51]
	v_mfma_f32_16x16x32_bf16 v[40:43], v[180:183], v[188:191], v[40:43]
	v_mfma_f32_16x16x32_bf16 v[32:35], v[170:173], v[196:199], v[32:35]
	v_mfma_f32_16x16x32_bf16 v[24:27], v[180:183], v[196:199], v[24:27]
	v_mfma_f32_16x16x32_bf16 v[16:19], v[170:173], v[204:207], v[16:19]
	v_mfma_f32_16x16x32_bf16 v[8:11], v[180:183], v[204:207], v[8:11]
	v_mfma_f32_16x16x32_bf16 v[4:7], v[170:173], v[212:215], v[4:7]
	v_mfma_f32_16x16x32_bf16 v[0:3], v[180:183], v[212:215], v[0:3]
	v_mfma_f32_16x16x32_bf16 v[48:51], v[176:179], v[192:195], v[48:51]
	v_mfma_f32_16x16x32_bf16 v[40:43], v[184:187], v[192:195], v[40:43]
	v_mfma_f32_16x16x32_bf16 v[32:35], v[176:179], v[200:203], v[32:35]
	v_mfma_f32_16x16x32_bf16 v[24:27], v[184:187], v[200:203], v[24:27]
	v_mfma_f32_16x16x32_bf16 v[16:19], v[176:179], v[208:211], v[16:19]
	v_mfma_f32_16x16x32_bf16 v[8:11], v[184:187], v[208:211], v[8:11]
	v_mfma_f32_16x16x32_bf16 v[4:7], v[176:179], v[216:219], v[4:7]
	v_mfma_f32_16x16x32_bf16 v[0:3], v[184:187], v[216:219], v[0:3]
	s_setprio 0
	s_barrier
	s_add_i32 s65, s65, 2
	s_add_u32 s38, s38, 0x100
	s_addc_u32 s39, s39, 0
	s_add_u32 s62, s62, 0x100
	s_addc_u32 s63, s63, 0
	s_cmp_gt_u32 s65, 13
	s_cbranch_scc0 .LBB0_292

.Lp4_nowait:
	s_ashr_i32 s27, s26, 31
	s_lshl_b64 s[28:29], s[26:27], 19
	s_add_u32 s28, s4, s28
	s_addc_u32 s29, s5, s29
	s_and_b64 s[30:31], s[8:9], exec
	s_cselect_b32 s27, s29, s35
	s_cselect_b32 s58, s28, s34
	s_ashr_i32 s25, s24, 31
	s_lshl_b64 s[30:31], s[24:25], 19
	s_add_u32 s30, s40, s30
	s_addc_u32 s31, s41, s31
	s_and_b64 s[38:39], s[8:9], exec
	s_cselect_b32 s25, s31, s37
	s_cselect_b32 s59, s30, s36
	s_add_u32 s34, s34, 0x40080
	s_addc_u32 s35, s35, 0
	s_add_u32 s60, s36, 0x100
	v_mov_b32_e32 v8, 0
	s_addc_u32 s61, s37, 0
	s_mov_b32 s62, -2
	s_waitcnt vmcnt(0)
	ds_read_b128 v[144:147], v151
	ds_read_b128 v[156:159], v151 offset:1024
	ds_read_b128 v[160:163], v151 offset:2048
	ds_read_b128 v[164:167], v151 offset:3072
	ds_read_b128 v[168:171], v152
	ds_read_b128 v[176:179], v152 offset:1024
	ds_read_b128 v[180:183], v152 offset:2048
	ds_read_b128 v[184:187], v152 offset:3072
	s_add_u32 s36, s34, 0xfffc0080
	s_addc_u32 s37, s35, -1
	s_cmp_eq_u32 s62, 12
	s_cselect_b32 s39, s27, s37
	s_cselect_b32 s38, s58, s36
	s_cselect_b32 s37, s25, s61
	s_cselect_b32 s36, s59, s60
	v_lshl_add_u64 v[172:173], s[34:35], 0, v[136:137]
	s_add_i32 m0, s45, 0xc000
	ds_read_b128 v[188:191], v153
	ds_read_b128 v[192:195], v153 offset:1024
	ds_read_b128 v[196:199], v153 offset:2048
	ds_read_b128 v[200:203], v153 offset:3072
	ds_read_b128 v[204:207], v153 offset:4096
	ds_read_b128 v[208:211], v153 offset:5120
	ds_read_b128 v[212:215], v153 offset:6144
	ds_read_b128 v[216:219], v153 offset:7168
	global_load_lds_dwordx4 v[172:173], off
	v_lshl_add_u64 v[172:173], s[34:35], 0, v[138:139]
	s_add_i32 m0, s45, 0xe000
	s_nop 0
	global_load_lds_dwordx4 v[172:173], off
	s_waitcnt vmcnt(8)
	s_waitcnt lgkmcnt(0)
	s_barrier
	s_setprio 1
	s_waitcnt lgkmcnt(0)
	v_mfma_f32_16x16x32_bf16 v[116:119], v[144:147], v[188:191], 0
	v_mfma_f32_16x16x32_bf16 v[112:115], v[160:163], v[188:191], 0
	v_mfma_f32_16x16x32_bf16 v[104:107], v[144:147], v[196:199], 0
	v_mfma_f32_16x16x32_bf16 v[96:99], v[160:163], v[196:199], 0
	v_mfma_f32_16x16x32_bf16 v[88:91], v[144:147], v[204:207], 0
	v_mfma_f32_16x16x32_bf16 v[80:83], v[160:163], v[204:207], 0
	v_mfma_f32_16x16x32_bf16 v[72:75], v[144:147], v[212:215], 0
	v_mfma_f32_16x16x32_bf16 v[64:67], v[160:163], v[212:215], 0
	v_mfma_f32_16x16x32_bf16 v[116:119], v[156:159], v[192:195], v[116:119]
	v_mfma_f32_16x16x32_bf16 v[112:115], v[164:167], v[192:195], v[112:115]
	v_mfma_f32_16x16x32_bf16 v[104:107], v[156:159], v[200:203], v[104:107]
	v_mfma_f32_16x16x32_bf16 v[96:99], v[164:167], v[200:203], v[96:99]
	v_mfma_f32_16x16x32_bf16 v[88:91], v[156:159], v[208:211], v[88:91]
	v_mfma_f32_16x16x32_bf16 v[80:83], v[164:167], v[208:211], v[80:83]
	v_mfma_f32_16x16x32_bf16 v[72:75], v[156:159], v[216:219], v[72:75]
	v_mfma_f32_16x16x32_bf16 v[64:67], v[164:167], v[216:219], v[64:67]
	s_setprio 0
	s_setprio 1
	v_mfma_f32_16x16x32_bf16 v[124:127], v[168:171], v[188:191], 0
	v_mfma_f32_16x16x32_bf16 v[120:123], v[180:183], v[188:191], 0
	v_mfma_f32_16x16x32_bf16 v[108:111], v[168:171], v[196:199], 0
	v_mfma_f32_16x16x32_bf16 v[100:103], v[180:183], v[196:199], 0
	v_mfma_f32_16x16x32_bf16 v[92:95], v[168:171], v[204:207], 0
	v_mfma_f32_16x16x32_bf16 v[84:87], v[180:183], v[204:207], 0
	v_mfma_f32_16x16x32_bf16 v[76:79], v[168:171], v[212:215], 0
	v_mfma_f32_16x16x32_bf16 v[68:71], v[180:183], v[212:215], 0
	v_mfma_f32_16x16x32_bf16 v[124:127], v[176:179], v[192:195], v[124:127]
	v_mfma_f32_16x16x32_bf16 v[120:123], v[184:187], v[192:195], v[120:123]
	v_mfma_f32_16x16x32_bf16 v[108:111], v[176:179], v[200:203], v[108:111]
	v_mfma_f32_16x16x32_bf16 v[100:103], v[184:187], v[200:203], v[100:103]
	v_mfma_f32_16x16x32_bf16 v[92:95], v[176:179], v[208:211], v[92:95]
	v_mfma_f32_16x16x32_bf16 v[84:87], v[184:187], v[208:211], v[84:87]
	v_mfma_f32_16x16x32_bf16 v[76:79], v[176:179], v[216:219], v[76:79]
	v_mfma_f32_16x16x32_bf16 v[68:71], v[184:187], v[216:219], v[68:71]
	s_setprio 0
	s_barrier
	s_add_i32 s63, s54, s42
	v_lshl_add_u64 v[172:173], s[36:37], 0, v[132:133]
	s_mov_b32 m0, s63
	ds_read_b128 v[188:191], v153 offset:16384
	ds_read_b128 v[192:195], v153 offset:17408
	ds_read_b128 v[196:199], v153 offset:18432
	ds_read_b128 v[200:203], v153 offset:19456
	ds_read_b128 v[204:207], v153 offset:20480
	ds_read_b128 v[208:211], v153 offset:21504
	ds_read_b128 v[212:215], v153 offset:22528
	ds_read_b128 v[216:219], v153 offset:23552
	global_load_lds_dwordx4 v[172:173], off
	s_add_i32 m0, s63, 0x2000
	s_add_u32 s68, s36, 0x40000
	v_lshl_add_u64 v[220:221], s[36:37], 0, v[128:129]
	s_addc_u32 s69, s37, 0
	s_add_i32 s63, s55, s42
	global_load_lds_dwordx4 v[220:221], off
	v_lshl_add_u64 v[222:223], s[68:69], 0, v[132:133]
	s_mov_b32 m0, s63
	v_lshl_add_u64 v[224:225], s[38:39], 0, v[130:131]
	global_load_lds_dwordx4 v[222:223], off
	v_lshl_add_u64 v[222:223], s[68:69], 0, v[128:129]
	s_add_i32 m0, s63, 0x2000
	s_nop 0
	global_load_lds_dwordx4 v[222:223], off
	v_lshl_add_u64 v[222:223], s[38:39], 0, v[134:135]
	s_mov_b32 m0, s45
	s_nop 0
	global_load_lds_dwordx4 v[222:223], off
	s_mov_b32 m0, s46
	s_nop 0
	global_load_lds_dwordx4 v[224:225], off
	s_waitcnt vmcnt(8)
	s_waitcnt lgkmcnt(0)
	s_barrier
	s_setprio 1
	s_waitcnt lgkmcnt(0)
	v_mfma_f32_16x16x32_bf16 v[56:59], v[144:147], v[188:191], 0
	v_mfma_f32_16x16x32_bf16 v[48:51], v[160:163], v[188:191], 0
	v_mfma_f32_16x16x32_bf16 v[40:43], v[144:147], v[196:199], 0
	v_mfma_f32_16x16x32_bf16 v[32:35], v[160:163], v[196:199], 0
	v_mfma_f32_16x16x32_bf16 v[24:27], v[144:147], v[204:207], 0
	v_mfma_f32_16x16x32_bf16 v[16:19], v[160:163], v[204:207], 0
	v_mfma_f32_16x16x32_bf16 v[4:7], v[144:147], v[212:215], 0
	v_mfma_f32_16x16x32_bf16 v[0:3], v[160:163], v[212:215], 0
	v_mfma_f32_16x16x32_bf16 v[56:59], v[156:159], v[192:195], v[56:59]
	v_mfma_f32_16x16x32_bf16 v[48:51], v[164:167], v[192:195], v[48:51]
	v_mfma_f32_16x16x32_bf16 v[40:43], v[156:159], v[200:203], v[40:43]
	v_mfma_f32_16x16x32_bf16 v[32:35], v[164:167], v[200:203], v[32:35]
	v_mfma_f32_16x16x32_bf16 v[24:27], v[156:159], v[208:211], v[24:27]
	v_mfma_f32_16x16x32_bf16 v[16:19], v[164:167], v[208:211], v[16:19]
	v_mfma_f32_16x16x32_bf16 v[4:7], v[156:159], v[216:219], v[4:7]
	v_mfma_f32_16x16x32_bf16 v[0:3], v[164:167], v[216:219], v[0:3]
	s_setprio 0
	s_setprio 1
	v_mfma_f32_16x16x32_bf16 v[60:63], v[168:171], v[188:191], 0
	v_mfma_f32_16x16x32_bf16 v[52:55], v[180:183], v[188:191], 0
	v_mfma_f32_16x16x32_bf16 v[44:47], v[168:171], v[196:199], 0
	v_mfma_f32_16x16x32_bf16 v[36:39], v[180:183], v[196:199], 0
	v_mfma_f32_16x16x32_bf16 v[28:31], v[168:171], v[204:207], 0
	v_mfma_f32_16x16x32_bf16 v[20:23], v[180:183], v[204:207], 0
	v_mfma_f32_16x16x32_bf16 v[12:15], v[168:171], v[212:215], 0
	v_mfma_f32_16x16x32_bf16 v[8:11], v[180:183], v[212:215], 0
	v_mfma_f32_16x16x32_bf16 v[60:63], v[176:179], v[192:195], v[60:63]
	v_mfma_f32_16x16x32_bf16 v[52:55], v[184:187], v[192:195], v[52:55]
	v_mfma_f32_16x16x32_bf16 v[44:47], v[176:179], v[200:203], v[44:47]
	v_mfma_f32_16x16x32_bf16 v[36:39], v[184:187], v[200:203], v[36:39]
	v_mfma_f32_16x16x32_bf16 v[28:31], v[176:179], v[208:211], v[28:31]
	v_mfma_f32_16x16x32_bf16 v[20:23], v[184:187], v[208:211], v[20:23]
	v_mfma_f32_16x16x32_bf16 v[12:15], v[176:179], v[216:219], v[12:15]
	v_mfma_f32_16x16x32_bf16 v[8:11], v[184:187], v[216:219], v[8:11]
	s_setprio 0
	s_barrier
	s_add_i32 s63, 0, 0x18000
	v_add_u32_e32 v155, s63, v149
	s_add_i32 s65, 0, 0x1c000
	ds_read_b128 v[144:147], v155
	ds_read_b128 v[156:159], v155 offset:1024
	ds_read_b128 v[160:163], v155 offset:2048
	ds_read_b128 v[164:167], v155 offset:3072
	v_add_u32_e32 v155, s65, v149
	ds_read_b128 v[168:171], v155
	ds_read_b128 v[176:179], v155 offset:1024
	ds_read_b128 v[180:183], v155 offset:2048
	ds_read_b128 v[184:187], v155 offset:3072
	s_add_u32 s38, s38, 0x40000
	s_addc_u32 s39, s39, 0
	s_mov_b32 m0, s47
	v_lshl_add_u64 v[226:227], s[38:39], 0, v[134:135]
	ds_read_b128 v[188:191], v153 offset:32768
	ds_read_b128 v[192:195], v153 offset:33792
	ds_read_b128 v[196:199], v153 offset:34816
	ds_read_b128 v[200:203], v153 offset:35840
	ds_read_b128 v[204:207], v153 offset:36864
	ds_read_b128 v[208:211], v153 offset:37888
	ds_read_b128 v[212:215], v153 offset:38912
	ds_read_b128 v[216:219], v153 offset:39936
	global_load_lds_dwordx4 v[226:227], off
	v_lshl_add_u64 v[226:227], s[38:39], 0, v[130:131]
	s_mov_b32 m0, s48
	s_nop 0
	global_load_lds_dwordx4 v[226:227], off
	s_waitcnt vmcnt(8)
	s_waitcnt lgkmcnt(0)
	s_barrier
	s_setprio 1
	s_waitcnt lgkmcnt(0)
	v_mfma_f32_16x16x32_bf16 v[116:119], v[144:147], v[188:191], v[116:119]
	v_mfma_f32_16x16x32_bf16 v[112:115], v[160:163], v[188:191], v[112:115]
	v_mfma_f32_16x16x32_bf16 v[104:107], v[144:147], v[196:199], v[104:107]
	v_mfma_f32_16x16x32_bf16 v[96:99], v[160:163], v[196:199], v[96:99]
	v_mfma_f32_16x16x32_bf16 v[88:91], v[144:147], v[204:207], v[88:91]
	v_mfma_f32_16x16x32_bf16 v[80:83], v[160:163], v[204:207], v[80:83]
	v_mfma_f32_16x16x32_bf16 v[72:75], v[144:147], v[212:215], v[72:75]
	v_mfma_f32_16x16x32_bf16 v[64:67], v[160:163], v[212:215], v[64:67]
	v_mfma_f32_16x16x32_bf16 v[116:119], v[156:159], v[192:195], v[116:119]
	v_mfma_f32_16x16x32_bf16 v[112:115], v[164:167], v[192:195], v[112:115]
	v_mfma_f32_16x16x32_bf16 v[104:107], v[156:159], v[200:203], v[104:107]
	v_mfma_f32_16x16x32_bf16 v[96:99], v[164:167], v[200:203], v[96:99]
	v_mfma_f32_16x16x32_bf16 v[88:91], v[156:159], v[208:211], v[88:91]
	v_mfma_f32_16x16x32_bf16 v[80:83], v[164:167], v[208:211], v[80:83]
	v_mfma_f32_16x16x32_bf16 v[72:75], v[156:159], v[216:219], v[72:75]
	v_mfma_f32_16x16x32_bf16 v[64:67], v[164:167], v[216:219], v[64:67]
	s_setprio 0
	s_setprio 1
	v_mfma_f32_16x16x32_bf16 v[124:127], v[168:171], v[188:191], v[124:127]
	v_mfma_f32_16x16x32_bf16 v[120:123], v[180:183], v[188:191], v[120:123]
	v_mfma_f32_16x16x32_bf16 v[108:111], v[168:171], v[196:199], v[108:111]
	v_mfma_f32_16x16x32_bf16 v[100:103], v[180:183], v[196:199], v[100:103]
	v_mfma_f32_16x16x32_bf16 v[92:95], v[168:171], v[204:207], v[92:95]
	v_mfma_f32_16x16x32_bf16 v[84:87], v[180:183], v[204:207], v[84:87]
	v_mfma_f32_16x16x32_bf16 v[76:79], v[168:171], v[212:215], v[76:79]
	v_mfma_f32_16x16x32_bf16 v[68:71], v[180:183], v[212:215], v[68:71]
	v_mfma_f32_16x16x32_bf16 v[124:127], v[176:179], v[192:195], v[124:127]
	v_mfma_f32_16x16x32_bf16 v[120:123], v[184:187], v[192:195], v[120:123]
	v_mfma_f32_16x16x32_bf16 v[108:111], v[176:179], v[200:203], v[108:111]
	v_mfma_f32_16x16x32_bf16 v[100:103], v[184:187], v[200:203], v[100:103]
	v_mfma_f32_16x16x32_bf16 v[92:95], v[176:179], v[208:211], v[92:95]
	v_mfma_f32_16x16x32_bf16 v[84:87], v[184:187], v[208:211], v[84:87]
	v_mfma_f32_16x16x32_bf16 v[76:79], v[176:179], v[216:219], v[76:79]
	v_mfma_f32_16x16x32_bf16 v[68:71], v[184:187], v[216:219], v[68:71]
	s_setprio 0
	s_barrier
	s_add_i32 s38, s63, s42
	v_lshl_add_u64 v[172:173], v[172:173], 0, s[20:21]
	s_mov_b32 m0, s38
	ds_read_b128 v[188:191], v153 offset:49152
	ds_read_b128 v[192:195], v153 offset:50176
	ds_read_b128 v[196:199], v153 offset:51200
	ds_read_b128 v[200:203], v153 offset:52224
	ds_read_b128 v[204:207], v153 offset:53248
	ds_read_b128 v[208:211], v153 offset:54272
	ds_read_b128 v[212:215], v153 offset:55296
	ds_read_b128 v[216:219], v153 offset:56320
	global_load_lds_dwordx4 v[172:173], off
	s_add_i32 m0, s38, 0x2000
	s_add_u32 s36, s36, 0x40080
	v_lshl_add_u64 v[172:173], v[220:221], 0, s[20:21]
	s_addc_u32 s37, s37, 0
	s_add_i32 s38, s65, s42
	global_load_lds_dwordx4 v[172:173], off
	v_lshl_add_u64 v[172:173], s[36:37], 0, v[132:133]
	s_mov_b32 m0, s38
	s_nop 0
	global_load_lds_dwordx4 v[172:173], off
	v_lshl_add_u64 v[172:173], s[36:37], 0, v[128:129]
	s_add_i32 m0, s38, 0x2000
	s_nop 0
	global_load_lds_dwordx4 v[172:173], off
	v_lshl_add_u64 v[172:173], v[222:223], 0, s[20:21]
	s_mov_b32 m0, s50
	s_nop 0
	global_load_lds_dwordx4 v[172:173], off
	v_lshl_add_u64 v[172:173], v[224:225], 0, s[20:21]
	s_mov_b32 m0, s51
	s_nop 0
	global_load_lds_dwordx4 v[172:173], off
	s_waitcnt vmcnt(8)
	s_waitcnt lgkmcnt(0)
	s_barrier
	s_setprio 1
	s_waitcnt lgkmcnt(0)
	v_mfma_f32_16x16x32_bf16 v[56:59], v[144:147], v[188:191], v[56:59]
	v_mfma_f32_16x16x32_bf16 v[48:51], v[160:163], v[188:191], v[48:51]
	v_mfma_f32_16x16x32_bf16 v[40:43], v[144:147], v[196:199], v[40:43]
	v_mfma_f32_16x16x32_bf16 v[32:35], v[160:163], v[196:199], v[32:35]
	v_mfma_f32_16x16x32_bf16 v[24:27], v[144:147], v[204:207], v[24:27]
	v_mfma_f32_16x16x32_bf16 v[16:19], v[160:163], v[204:207], v[16:19]
	v_mfma_f32_16x16x32_bf16 v[4:7], v[144:147], v[212:215], v[4:7]
	v_mfma_f32_16x16x32_bf16 v[0:3], v[160:163], v[212:215], v[0:3]
	v_mfma_f32_16x16x32_bf16 v[56:59], v[156:159], v[192:195], v[56:59]
	v_mfma_f32_16x16x32_bf16 v[48:51], v[164:167], v[192:195], v[48:51]
	v_mfma_f32_16x16x32_bf16 v[40:43], v[156:159], v[200:203], v[40:43]
	v_mfma_f32_16x16x32_bf16 v[32:35], v[164:167], v[200:203], v[32:35]
	v_mfma_f32_16x16x32_bf16 v[24:27], v[156:159], v[208:211], v[24:27]
	v_mfma_f32_16x16x32_bf16 v[16:19], v[164:167], v[208:211], v[16:19]
	v_mfma_f32_16x16x32_bf16 v[4:7], v[156:159], v[216:219], v[4:7]
	v_mfma_f32_16x16x32_bf16 v[0:3], v[164:167], v[216:219], v[0:3]
	s_setprio 0
	s_setprio 1
	v_mfma_f32_16x16x32_bf16 v[60:63], v[168:171], v[188:191], v[60:63]
	v_mfma_f32_16x16x32_bf16 v[52:55], v[180:183], v[188:191], v[52:55]
	v_mfma_f32_16x16x32_bf16 v[44:47], v[168:171], v[196:199], v[44:47]
	v_mfma_f32_16x16x32_bf16 v[36:39], v[180:183], v[196:199], v[36:39]
	v_mfma_f32_16x16x32_bf16 v[28:31], v[168:171], v[204:207], v[28:31]
	v_mfma_f32_16x16x32_bf16 v[20:23], v[180:183], v[204:207], v[20:23]
	v_mfma_f32_16x16x32_bf16 v[12:15], v[168:171], v[212:215], v[12:15]
	v_mfma_f32_16x16x32_bf16 v[8:11], v[180:183], v[212:215], v[8:11]
	v_mfma_f32_16x16x32_bf16 v[60:63], v[176:179], v[192:195], v[60:63]
	v_mfma_f32_16x16x32_bf16 v[52:55], v[184:187], v[192:195], v[52:55]
	v_mfma_f32_16x16x32_bf16 v[44:47], v[176:179], v[200:203], v[44:47]
	v_mfma_f32_16x16x32_bf16 v[36:39], v[184:187], v[200:203], v[36:39]
	v_mfma_f32_16x16x32_bf16 v[28:31], v[176:179], v[208:211], v[28:31]
	v_mfma_f32_16x16x32_bf16 v[20:23], v[184:187], v[208:211], v[20:23]
	v_mfma_f32_16x16x32_bf16 v[12:15], v[176:179], v[216:219], v[12:15]
	v_mfma_f32_16x16x32_bf16 v[8:11], v[184:187], v[216:219], v[8:11]
	s_setprio 0
	s_barrier
	s_add_i32 s62, s62, 2
	s_add_u32 s34, s34, 0x100
	s_addc_u32 s35, s35, 0
	s_add_u32 s60, s60, 0x100
	s_addc_u32 s61, s61, 0
	s_cmp_gt_u32 s62, 13
	s_cbranch_scc0 .LBB0_1829
